# speedup vs baseline: 1.0108x; 1.0073x over previous
; #define WAIT_V(n) asm volatile("s_waitcnt vmcnt(%0)" ::"n"(n) : "memory")
; #define BAR8 __builtin_amdgcn_s_barrier()
; template <int EPI> ...
;     ...
;     if constexpr (EPI == EPI_RES) {
; #pragma unroll
;       for (int m = 0; m < 8; ++m)
; #pragma unroll
;         for (int n = 0; n < 4; ++n) asm volatile("" : "+v"(acc[m][n]));
;     } else {
; #pragma unroll
;       for (int m = 0; m < 8; ++m)
; #pragma unroll
;         for (int n = 0; n < 4; ++n) acc[m][n] = f32x4{0.f, 0.f, 0.f, 0.f};
;     }
;     {
;       bf16x8 At[4][2], B0[2][2], B1[2][2];
;       if (wr == 1) BAR8;
;       BAR8;
;       STAGE_Bm(1, 0, Bb, 1); STAGE_A(1, 0, Ab, 1); STAGE_Bm(1, 1, Bb, 1);
;       WAIT_V(6); BAR8;
.LBB0_139:
	s_or_b64 exec, exec, s[22:23]
	v_lshl_add_u64 v[138:139], s[6:7], 0, v[4:5]
	s_mov_b64 s[6:7], 0x80
	s_mov_b32 m0, s57
	v_lshl_add_u64 v[8:9], v[138:139], 0, s[6:7]
	s_mov_b64 s[22:23], 0x40080
	s_barrier
	global_load_lds_dwordx4 v[8:9], off
	v_lshl_add_u64 v[8:9], v[138:139], 0, s[22:23]
	s_mov_b32 m0, s58
	v_lshl_add_u64 v[136:137], s[16:17], 0, v[0:1]
	global_load_lds_dwordx4 v[8:9], off
	v_lshl_add_u64 v[8:9], v[136:137], 0, s[6:7]
	s_mov_b32 m0, s59
	s_mov_b64 s[6:7], 0x10080
	global_load_lds_dwordx4 v[8:9], off
	v_lshl_add_u64 v[8:9], v[136:137], 0, s[22:23]
	s_mov_b32 m0, s65
	s_mov_b64 s[34:35], 0x40080
	global_load_lds_dwordx4 v[8:9], off
	v_lshl_add_u64 v[8:9], v[138:139], 0, s[6:7]
	s_mov_b32 m0, s70
	s_mov_b64 s[6:7], 0x50080
	global_load_lds_dwordx4 v[8:9], off
	v_lshl_add_u64 v[8:9], v[138:139], 0, s[6:7]
	s_mov_b32 m0, s71
	s_mov_b64 s[6:7], 0x20000
	global_load_lds_dwordx4 v[8:9], off
	v_mov_b32_e32 v8, 0
	v_lshl_add_u64 v[140:141], v[136:137], 0, s[6:7]
	v_lshl_add_u64 v[142:143], v[138:139], 0, s[44:45]
	s_mov_b32 s16, -2
	v_mov_b32_e32 v9, v8
	v_mov_b32_e32 v10, v8
	v_mov_b32_e32 v11, v8
	v_mov_b32_e32 v12, v8
	v_mov_b32_e32 v13, v8
	v_mov_b32_e32 v14, v8
	v_mov_b32_e32 v15, v8
	v_mov_b32_e32 v24, v8
	v_mov_b32_e32 v25, v8
	v_mov_b32_e32 v26, v8
	v_mov_b32_e32 v27, v8
	v_mov_b32_e32 v36, v8
	v_mov_b32_e32 v37, v8
	v_mov_b32_e32 v38, v8
	v_mov_b32_e32 v39, v8
	v_mov_b32_e32 v16, v8
	v_mov_b32_e32 v17, v8
	v_mov_b32_e32 v18, v8
	v_mov_b32_e32 v19, v8
	v_mov_b32_e32 v20, v8
	v_mov_b32_e32 v21, v8
	v_mov_b32_e32 v22, v8
	v_mov_b32_e32 v23, v8
	v_mov_b32_e32 v64, v8
	v_mov_b32_e32 v65, v8
	v_mov_b32_e32 v66, v8
	v_mov_b32_e32 v67, v8
	v_mov_b32_e32 v72, v8
	v_mov_b32_e32 v73, v8
	v_mov_b32_e32 v74, v8
	v_mov_b32_e32 v75, v8
	v_mov_b32_e32 v40, v8
	v_mov_b32_e32 v41, v8
	v_mov_b32_e32 v42, v8
	v_mov_b32_e32 v43, v8
	v_mov_b32_e32 v44, v8
	v_mov_b32_e32 v45, v8
	v_mov_b32_e32 v46, v8
	v_mov_b32_e32 v47, v8
	v_mov_b32_e32 v108, v8
	v_mov_b32_e32 v109, v8
	v_mov_b32_e32 v110, v8
	v_mov_b32_e32 v111, v8
	v_mov_b32_e32 v116, v8
	v_mov_b32_e32 v117, v8
	v_mov_b32_e32 v118, v8
	v_mov_b32_e32 v119, v8
	v_mov_b32_e32 v76, v8
	v_mov_b32_e32 v77, v8
	v_mov_b32_e32 v78, v8
	v_mov_b32_e32 v79, v8
	v_mov_b32_e32 v92, v8
	v_mov_b32_e32 v93, v8
	v_mov_b32_e32 v94, v8
	v_mov_b32_e32 v95, v8
	v_mov_b32_e32 v128, v8
	v_mov_b32_e32 v129, v8
	v_mov_b32_e32 v130, v8
	v_mov_b32_e32 v131, v8
	v_mov_b32_e32 v132, v8
	v_mov_b32_e32 v133, v8
	v_mov_b32_e32 v134, v8
	v_mov_b32_e32 v135, v8
	v_mov_b32_e32 v48, v8
	v_mov_b32_e32 v49, v8
	v_mov_b32_e32 v50, v8
	v_mov_b32_e32 v51, v8
	v_mov_b32_e32 v56, v8
	v_mov_b32_e32 v57, v8
	v_mov_b32_e32 v58, v8
	v_mov_b32_e32 v59, v8
	v_mov_b32_e32 v28, v8
	v_mov_b32_e32 v29, v8
	v_mov_b32_e32 v30, v8
	v_mov_b32_e32 v31, v8
	v_mov_b32_e32 v32, v8
	v_mov_b32_e32 v33, v8
	v_mov_b32_e32 v34, v8
	v_mov_b32_e32 v35, v8
	v_mov_b32_e32 v68, v8
	v_mov_b32_e32 v69, v8
	v_mov_b32_e32 v70, v8
	v_mov_b32_e32 v71, v8
	v_mov_b32_e32 v84, v8
	v_mov_b32_e32 v85, v8
	v_mov_b32_e32 v86, v8
	v_mov_b32_e32 v87, v8
	v_mov_b32_e32 v52, v8
	v_mov_b32_e32 v53, v8
	v_mov_b32_e32 v54, v8
	v_mov_b32_e32 v55, v8
	v_mov_b32_e32 v60, v8
	v_mov_b32_e32 v61, v8
	v_mov_b32_e32 v62, v8
	v_mov_b32_e32 v63, v8
	v_mov_b32_e32 v96, v8
	v_mov_b32_e32 v97, v8
	v_mov_b32_e32 v98, v8
	v_mov_b32_e32 v99, v8
	v_mov_b32_e32 v104, v8
	v_mov_b32_e32 v105, v8
	v_mov_b32_e32 v106, v8
	v_mov_b32_e32 v107, v8
	v_mov_b32_e32 v80, v8
	v_mov_b32_e32 v81, v8
	v_mov_b32_e32 v82, v8
	v_mov_b32_e32 v83, v8
	v_mov_b32_e32 v88, v8
	v_mov_b32_e32 v89, v8
	v_mov_b32_e32 v90, v8
	v_mov_b32_e32 v91, v8
	v_mov_b32_e32 v120, v8
	v_mov_b32_e32 v121, v8
	v_mov_b32_e32 v122, v8
	v_mov_b32_e32 v123, v8
	v_mov_b32_e32 v124, v8
	v_mov_b32_e32 v125, v8
	v_mov_b32_e32 v126, v8
	v_mov_b32_e32 v127, v8
	v_mov_b32_e32 v100, v8
	v_mov_b32_e32 v101, v8
	v_mov_b32_e32 v102, v8
	v_mov_b32_e32 v103, v8
	v_mov_b32_e32 v112, v8
	v_mov_b32_e32 v113, v8
	v_mov_b32_e32 v114, v8
	v_mov_b32_e32 v115, v8
	s_barrier

;   __device__ __forceinline__ u16* proj() const { return (u16*)(ws + 185 * MB); }
; __device__ __forceinline__ float bflo(unsigned u) { return __uint_as_float(u << 16); }
; __device__ __forceinline__ float bfhi(unsigned u) { return __uint_as_float(u & 0xffff0000u); }
; __device__ __forceinline__ void sb_phase(const Params& p, char* shm, int wv, int vb) {
;     ...
;     sb_decode(idx, b, h, qb);
;     const int ntile = 4 * qb + 4;
;     const int q0 = qb * 256 + w * 32;
;     const int lastTile = (q0 + 30) >> 6;
;     const bool more = (idx + nblk) < 1024;
;     if (more) SB_FETCH(idx + nblk);
;     bf16x8 qf[2][2];
; #pragma unroll
;     for (int n = 0; n < 2; ++n)
; #pragma unroll
;       for (int ks = 0; ks < 2; ++ks) {
;         const u32x4 raw = *(const u32x4*)(p.proj() + ((long)b * SEQ + q0 + n * 16 + fr) * INW + h * 64 + ks * 32 + fq * 8);
;         unsigned o[4];
; #pragma unroll
;         for (int j = 0; j < 4; ++j) o[j] = pack2(bflo(raw[j]) * SC2, bfhi(raw[j]) * SC2);
;         qf[n][ks] = mk8(o[0], o[1], o[2], o[3]);
;       }
.LBB0_366:
	s_lshl_b32 s90, s51, 8
	s_and_b32 s92, s13, 7
	v_add_u32_e32 v0, s90, v186
	s_lshl_b32 s26, s92, 12
	s_mov_b32 s27, s52
	v_ashrrev_i32_e32 v1, 31, v0
	s_lshl_b32 s6, s12, 6
	v_lshl_add_u64 v[178:179], v[0:1], 0, s[26:27]
	s_and_b32 s27, s6, 0x1c0
	s_lshl_b32 s24, s27, 1
	s_mov_b32 s25, s52
	v_or_b32_e32 v178, v178, v164
	v_lshl_add_u64 v[68:69], v[172:173], 0, s[24:25]
	v_mad_u64_u32 v[76:77], s[6:7], v178, s88, v[68:69]
	v_mad_i32_i24 v77, v179, s88, v77
	s_mov_b64 s[6:7], 0x22000
	v_lshl_add_u64 v[80:81], v[76:77], 0, s[6:7]
	s_mov_b32 s6, 0x22000
	s_lshl_b32 s91, s51, 2
	global_load_dwordx4 v[68:71], v[76:77], off
	global_load_dwordx4 v[72:75], v[76:77], off offset:64
	global_load_dwordx4 v[76:79], v[80:81], off
	global_load_dwordx4 v[80:83], v[80:81], off offset:64
	s_waitcnt vmcnt(0)
	v_lshlrev_b32_e32 v84, 16, v68
	v_and_b32_e32 v85, 0xffff0000, v68
	v_pk_mul_f32 v[84:85], v[84:85], s[18:19] op_sel_hi:[1,0]
	s_nop 0
	v_cvt_pk_bf16_f32 v68, v84, v85
	v_lshlrev_b32_e32 v84, 16, v69
	v_and_b32_e32 v85, 0xffff0000, v69
	v_pk_mul_f32 v[84:85], v[84:85], s[18:19] op_sel_hi:[1,0]
	s_nop 0
	v_cvt_pk_bf16_f32 v69, v84, v85
	v_lshlrev_b32_e32 v84, 16, v70
	v_and_b32_e32 v85, 0xffff0000, v70
	v_pk_mul_f32 v[84:85], v[84:85], s[18:19] op_sel_hi:[1,0]
	s_nop 0
	v_cvt_pk_bf16_f32 v70, v84, v85
	v_lshlrev_b32_e32 v84, 16, v71
	v_and_b32_e32 v85, 0xffff0000, v71
	v_pk_mul_f32 v[84:85], v[84:85], s[18:19] op_sel_hi:[1,0]
	s_nop 0
	v_cvt_pk_bf16_f32 v71, v84, v85
	v_lshlrev_b32_e32 v84, 16, v72
	v_and_b32_e32 v85, 0xffff0000, v72
	v_pk_mul_f32 v[84:85], v[84:85], s[18:19] op_sel_hi:[1,0]
	s_nop 0
	v_cvt_pk_bf16_f32 v72, v84, v85
	v_lshlrev_b32_e32 v84, 16, v73
	v_and_b32_e32 v85, 0xffff0000, v73
	v_pk_mul_f32 v[84:85], v[84:85], s[18:19] op_sel_hi:[1,0]
	s_nop 0
	v_cvt_pk_bf16_f32 v73, v84, v85
	v_lshlrev_b32_e32 v84, 16, v74
	v_and_b32_e32 v85, 0xffff0000, v74
	v_pk_mul_f32 v[84:85], v[84:85], s[18:19] op_sel_hi:[1,0]
	s_nop 0
	v_cvt_pk_bf16_f32 v74, v84, v85
	v_lshlrev_b32_e32 v84, 16, v75
	v_and_b32_e32 v85, 0xffff0000, v75
	v_pk_mul_f32 v[84:85], v[84:85], s[18:19] op_sel_hi:[1,0]
	s_nop 0
	v_cvt_pk_bf16_f32 v75, v84, v85
	v_lshlrev_b32_e32 v84, 16, v76
	v_and_b32_e32 v85, 0xffff0000, v76
	v_pk_mul_f32 v[84:85], v[84:85], s[18:19] op_sel_hi:[1,0]
	s_nop 0
	v_cvt_pk_bf16_f32 v76, v84, v85
	v_lshlrev_b32_e32 v84, 16, v77
	v_and_b32_e32 v85, 0xffff0000, v77
	v_pk_mul_f32 v[84:85], v[84:85], s[18:19] op_sel_hi:[1,0]
	s_nop 0
	v_cvt_pk_bf16_f32 v77, v84, v85
	v_lshlrev_b32_e32 v84, 16, v78
	v_and_b32_e32 v85, 0xffff0000, v78
	v_pk_mul_f32 v[84:85], v[84:85], s[18:19] op_sel_hi:[1,0]
	s_nop 0
	v_cvt_pk_bf16_f32 v78, v84, v85
	v_lshlrev_b32_e32 v84, 16, v79
	v_and_b32_e32 v85, 0xffff0000, v79
	v_pk_mul_f32 v[84:85], v[84:85], s[18:19] op_sel_hi:[1,0]
	s_nop 0
	v_cvt_pk_bf16_f32 v79, v84, v85
	v_lshlrev_b32_e32 v84, 16, v80
	v_and_b32_e32 v85, 0xffff0000, v80
	v_pk_mul_f32 v[84:85], v[84:85], s[18:19] op_sel_hi:[1,0]
	s_nop 0
	v_cvt_pk_bf16_f32 v80, v84, v85
	v_lshlrev_b32_e32 v84, 16, v81
	v_and_b32_e32 v85, 0xffff0000, v81
	v_pk_mul_f32 v[84:85], v[84:85], s[18:19] op_sel_hi:[1,0]
	s_nop 0
	v_cvt_pk_bf16_f32 v81, v84, v85
	v_lshlrev_b32_e32 v84, 16, v82
	v_and_b32_e32 v85, 0xffff0000, v82
	v_pk_mul_f32 v[84:85], v[84:85], s[18:19] op_sel_hi:[1,0]
	s_nop 0
	v_cvt_pk_bf16_f32 v82, v84, v85
	v_lshlrev_b32_e32 v84, 16, v83
	v_and_b32_e32 v85, 0xffff0000, v83
	v_pk_mul_f32 v[84:85], v[84:85], s[18:19] op_sel_hi:[1,0]
	s_nop 0
	v_cvt_pk_bf16_f32 v83, v84, v85
	s_add_i32 s65, s8, s37
	s_cmpk_lt_i32 s65, 0x400
	s_cselect_b64 s[22:23], -1, 0
	s_cmpk_gt_i32 s65, 0x3ff
	s_cselect_b64 s[0:1], -1, 0
	s_and_b64 vcc, exec, s[0:1]
	s_cbranch_vccnz .LBB0_389
	s_mov_b64 s[6:7], -1
	s_and_b64 vcc, exec, s[66:67]
	s_cbranch_vccz .LBB0_373
	s_ashr_i32 s9, s65, 8
	s_bfe_u32 s10, s65, 0x20006
	s_bitcmp0_b32 s65, 8
	s_cbranch_scc1 .LBB0_370
	s_lshl_b32 s6, s9, 2
	s_sub_i32 s6, s10, s6
	s_add_i32 s14, s6, 12
	s_mov_b64 s[6:7], 0

; __device__ __forceinline__ void sb_phase(const Params& p, char* shm, int wv, int vb) {
;     ...
;     f32x4 oacc[4][2];
; #pragma unroll
;     for (int mt = 0; mt < 4; ++mt)
; #pragma unroll
;       for (int n = 0; n < 2; ++n) oacc[mt][n] = zero4;
;     float carry[2] = {0.f, 0.f};
;     bool mydone = false;
;     const int npre = ntile < SB_NPRE ? ntile : SB_NPRE;
.LBB0_375:
	s_and_b32 s9, s9, 7
	v_lshl_add_u32 v3, s9, 12, v162
	v_mov_b64_e32 v[84:85], s[30:31]
	v_mad_i64_i32 v[84:85], s[10:11], v3, s88, v[84:85]
	s_lshl_b32 s6, s6, 6
	s_and_b32 s10, s6, 0x1c0
	s_lshl_b32 s6, s10, 1
	s_mov_b32 s7, s52
	v_lshl_add_u64 v[84:85], v[84:85], 0, s[6:7]
	v_lshlrev_b32_e32 v88, 1, v168
	v_mov_b32_e32 v89, v2
	v_lshl_add_u64 v[84:85], v[84:85], 0, v[88:89]
	s_mov_b64 s[6:7], 0xb900400
	v_lshl_add_u64 v[84:85], v[84:85], 0, s[6:7]
	s_lshl_b32 s6, s9, 9
	s_or_b32 s6, s10, s6
	v_add_u32_e32 v88, s6, v162
	s_lshl_b32 s8, s14, 8
	v_ashrrev_i32_e32 v89, 31, v88
	v_lshlrev_b64 v[88:89], 13, v[88:89]
	s_cmp_gt_i32 s14, -1
	s_cselect_b64 s[10:11], -1, 0
	s_cmp_lt_i32 s14, 0
	v_lshl_add_u64 v[88:89], v[174:175], 0, v[88:89]
	s_cbranch_scc1 .LBB0_377
	s_or_b32 s6, s8, 0xc0
	s_mov_b32 s9, s52
	v_mad_u64_u32 v[8:9], s[6:7], s6, v161, v[84:85]
	v_lshl_add_u64 v[10:11], s[8:9], 1, v[88:89]
	global_load_dwordx4 v[12:15], v[8:9], off
	s_nop 0
	global_load_dwordx4 v[8:11], v[10:11], off offset:384
.LBB0_377:
	v_cndmask_b32_e64 v3, 0, 1, s[10:11]
	v_cmp_ne_u32_e64 s[6:7], 1, v3
	s_andn2_b64 vcc, exec, s[10:11]
	s_cbranch_vccnz .LBB0_379
	s_or_b32 s9, s8, 0x80
	v_mad_u64_u32 v[16:17], s[10:11], s9, v161, v[84:85]
	s_mov_b32 s9, s52
	v_lshl_add_u64 v[18:19], s[8:9], 1, v[88:89]
	global_load_dwordx4 v[20:23], v[16:17], off
	s_nop 0
	global_load_dwordx4 v[16:19], v[18:19], off offset:256
.LBB0_379:
	s_and_b64 vcc, exec, s[6:7]
	s_cbranch_vccnz .LBB0_381
	s_or_b32 s9, s8, 64
	v_mad_u64_u32 v[24:25], s[10:11], s9, v161, v[84:85]
	s_mov_b32 s9, s52
	v_lshl_add_u64 v[26:27], s[8:9], 1, v[88:89]
	global_load_dwordx4 v[28:31], v[24:25], off
	s_nop 0
	global_load_dwordx4 v[24:27], v[26:27], off offset:128
.LBB0_381:
	s_and_b64 vcc, exec, s[6:7]
	s_cbranch_vccnz .LBB0_383
	s_mov_b32 s9, s52
	v_mad_u64_u32 v[32:33], s[6:7], s8, v161, v[84:85]
	v_lshl_add_u64 v[36:37], s[8:9], 1, v[88:89]
	global_load_dwordx4 v[32:35], v[32:33], off
	s_nop 0
	global_load_dwordx4 v[36:39], v[36:37], off
.LBB0_383:
	s_cmp_gt_i32 s14, 0
	s_cselect_b64 s[10:11], -1, 0
	s_cmp_lt_i32 s14, 1
	s_cbranch_scc1 .LBB0_385
	s_sub_i32 s6, s8, 64
	s_mov_b32 s7, s52
	v_mad_u64_u32 v[40:41], s[14:15], s6, v161, v[84:85]
	v_lshl_add_u64 v[44:45], s[6:7], 1, v[88:89]
	global_load_dwordx4 v[40:43], v[40:41], off
	s_nop 0
	global_load_dwordx4 v[44:47], v[44:45], off
.LBB0_385:
	v_cndmask_b32_e64 v3, 0, 1, s[10:11]
	v_cmp_ne_u32_e64 s[6:7], 1, v3
	s_andn2_b64 vcc, exec, s[10:11]
	s_cbranch_vccnz .LBB0_387
	s_add_i32 s10, s8, 0xffffff80
	s_mov_b32 s11, s52
	v_mad_u64_u32 v[48:49], s[14:15], s10, v161, v[84:85]
	v_lshl_add_u64 v[52:53], s[10:11], 1, v[88:89]
	global_load_dwordx4 v[48:51], v[48:49], off
	s_nop 0
	global_load_dwordx4 v[52:55], v[52:53], off
.LBB0_387:
	s_and_b64 vcc, exec, s[6:7]
	s_cbranch_vccnz .LBB0_389
	s_add_i32 s6, s8, 0xffffff40
	s_mov_b32 s7, s52
	v_mad_u64_u32 v[84:85], s[8:9], s6, v161, v[84:85]
	v_lshl_add_u64 v[60:61], s[6:7], 1, v[88:89]
	global_load_dwordx4 v[56:59], v[84:85], off
	s_nop 0
	global_load_dwordx4 v[60:63], v[60:61], off
.LBB0_389:
	s_cmp_lt_i32 s51, 0
	s_cbranch_scc1 .LBB0_402
	v_ashrrev_i32_e32 v156, 6, v0
	v_or_b32_e32 v157, v0, v164
	v_or_b32_e32 v0, v0, v166
	v_or_b32_e32 v1, 1, v0
	v_cmp_lt_i32_e32 vcc, v1, v157
	v_or_b32_e32 v1, 2, v0
	v_or_b32_e32 v0, 3, v0
	v_mov_b32_e32 v3, v2
	s_min_i32 s10, s91, 3
	v_cmp_lt_i32_e64 s[6:7], v1, v157
	v_cmp_lt_i32_e64 s[8:9], v0, v157
	v_add_u32_e32 v85, s90, v166
	v_mov_b32_e32 v0, v2
	v_mov_b32_e32 v1, v2
	v_mov_b64_e32 v[90:91], v[2:3]
	v_mov_b64_e32 v[94:95], v[2:3]
	v_mov_b64_e32 v[102:103], v[2:3]
	v_mov_b64_e32 v[106:107], v[2:3]
	v_mov_b64_e32 v[110:111], v[2:3]
	v_mov_b64_e32 v[114:115], v[2:3]
	v_mov_b64_e32 v[118:119], v[2:3]
	v_mov_b64_e32 v[122:123], v[2:3]
	s_or_b32 s25, s91, 3
	s_add_i32 s93, s10, 4
	s_mov_b32 s94, 0
	v_mov_b32_e32 v84, 0
	s_mov_b64 s[70:71], 0
	v_add_u32_e32 v158, v85, v191
	v_mov_b32_e32 v159, v190
	v_mov_b32_e32 v177, v171
	v_mov_b64_e32 v[88:89], v[0:1]
	v_mov_b64_e32 v[92:93], v[0:1]
	v_mov_b64_e32 v[100:101], v[0:1]
	v_mov_b64_e32 v[104:105], v[0:1]
	v_mov_b64_e32 v[108:109], v[0:1]
	v_mov_b64_e32 v[112:113], v[0:1]
	v_mov_b64_e32 v[116:117], v[0:1]
	v_mov_b64_e32 v[120:121], v[0:1]
	v_mov_b32_e32 v96, 0
	s_branch .LBB0_393

;   __device__ __forceinline__ u16* attn() const { return (u16*)(ws + 121 * MB); }
; __device__ __forceinline__ void sb_phase(const Params& p, char* shm, int wv, int vb) {
;     ...
; #pragma unroll
;     for (int n = 0; n < 2; ++n)
; #pragma unroll
;       for (int mt = 0; mt < 4; ++mt) {
;         u32x2 o = {pack2(oacc[mt][n][0], oacc[mt][n][1]), pack2(oacc[mt][n][2], oacc[mt][n][3])};
;         *(u32x2*)(p.attn() + ((long)b * SEQ + q0 + n * 16 + fr) * DM + h * 64 + mt * 16 + fq * 4) = o;
;       }
;     if (more) SB_COMMIT();
;     __syncthreads();
.LBB0_420:
	s_waitcnt vmcnt(0)
	v_readlane_b32 s6, v254, 36
	v_lshlrev_b64 v[0:1], 11, v[178:179]
	v_readlane_b32 s7, v254, 37
	s_mov_b32 s25, s52
	v_mov_b32_e32 v177, v2
	v_lshl_add_u64 v[70:71], s[6:7], 0, v[0:1]
	v_lshl_add_u64 v[70:71], v[70:71], 0, s[24:25]
	v_cvt_pk_bf16_f32 v68, v120, v121
	v_cvt_pk_bf16_f32 v69, v122, v123
	v_lshl_add_u64 v[70:71], v[70:71], 0, v[176:177]
	global_store_dwordx2 v[70:71], v[68:69], off
	v_lshl_add_u64 v[70:71], s[30:31], 0, v[0:1]
	v_lshl_add_u64 v[70:71], v[70:71], 0, s[24:25]
	v_lshl_add_u64 v[70:71], v[70:71], 0, v[176:177]
	s_mov_b32 s8, 0x7900000
	v_add_co_u32_e32 v70, vcc, s8, v70
	v_cvt_pk_bf16_f32 v68, v112, v113
	v_cvt_pk_bf16_f32 v69, v114, v115
	v_addc_co_u32_e32 v71, vcc, 0, v71, vcc
	global_store_dwordx2 v[70:71], v[68:69], off offset:32
	v_cvt_pk_bf16_f32 v68, v104, v105
	v_cvt_pk_bf16_f32 v69, v106, v107
	global_store_dwordx2 v[70:71], v[68:69], off offset:64
	v_cvt_pk_bf16_f32 v68, v92, v93
	v_cvt_pk_bf16_f32 v69, v94, v95
	v_or_b32_e32 v0, 0x8000, v0
	global_store_dwordx2 v[70:71], v[68:69], off offset:96
	v_lshl_add_u64 v[70:71], s[6:7], 0, v[0:1]
	v_lshl_add_u64 v[0:1], s[30:31], 0, v[0:1]
	v_lshl_add_u64 v[0:1], v[0:1], 0, s[24:25]
	v_lshl_add_u64 v[70:71], v[70:71], 0, s[24:25]
	v_lshl_add_u64 v[0:1], v[0:1], 0, v[176:177]
	v_cvt_pk_bf16_f32 v68, v116, v117
	v_cvt_pk_bf16_f32 v69, v118, v119
	v_lshl_add_u64 v[70:71], v[70:71], 0, v[176:177]
	v_add_co_u32_e32 v0, vcc, s8, v0
	global_store_dwordx2 v[70:71], v[68:69], off
	v_cvt_pk_bf16_f32 v68, v108, v109
	v_cvt_pk_bf16_f32 v69, v110, v111
	v_addc_co_u32_e32 v1, vcc, 0, v1, vcc
	global_store_dwordx2 v[0:1], v[68:69], off offset:32
	v_cvt_pk_bf16_f32 v68, v100, v101
	v_cvt_pk_bf16_f32 v69, v102, v103
	global_store_dwordx2 v[0:1], v[68:69], off offset:64
	v_cvt_pk_bf16_f32 v68, v88, v89
	v_cvt_pk_bf16_f32 v69, v90, v91
	s_andn2_b64 vcc, exec, s[22:23]
	global_store_dwordx2 v[0:1], v[68:69], off offset:96
	s_cbranch_vccnz .LBB0_357
	v_add_u32_e32 v0, 0x12000, v185
	ds_write_b128 v185, v[12:15]
	ds_write_b128 v185, v[8:11] offset:9216
	ds_write_b128 v185, v[20:23] offset:18432
	ds_write_b128 v185, v[16:19] offset:27648
	ds_write_b128 v185, v[28:31] offset:36864
	ds_write_b128 v185, v[24:27] offset:46080
	ds_write_b128 v185, v[32:35] offset:55296
	ds_write_b128 v185, v[36:39] offset:64512
	ds_write_b128 v0, v[40:43]
	v_add_u32_e32 v0, 0x14400, v185
	ds_write_b128 v0, v[44:47]
	v_add_u32_e32 v0, 0x16800, v185
	ds_write_b128 v0, v[48:51]
	v_add_u32_e32 v0, 0x18c00, v185
	ds_write_b128 v0, v[52:55]
	v_add_u32_e32 v0, 0x1b000, v185
	ds_write_b128 v0, v[56:59]
	v_add_u32_e32 v0, 0x1d400, v185
	ds_write_b128 v0, v[60:63]
	s_branch .LBB0_357

; #define WAIT_V(n) asm volatile("s_waitcnt vmcnt(%0)" ::"n"(n) : "memory")
; #define BAR8 __builtin_amdgcn_s_barrier()
; template <int EPI> ...
;     ...
;     if constexpr (EPI == EPI_RES) {
; #pragma unroll
;       for (int m = 0; m < 8; ++m)
; #pragma unroll
;         for (int n = 0; n < 4; ++n) asm volatile("" : "+v"(acc[m][n]));
;     } else {
; #pragma unroll
;       for (int m = 0; m < 8; ++m)
; #pragma unroll
;         for (int n = 0; n < 4; ++n) acc[m][n] = f32x4{0.f, 0.f, 0.f, 0.f};
;     }
;     {
;       bf16x8 At[4][2], B0[2][2], B1[2][2];
;       if (wr == 1) BAR8;
;       BAR8;
;       STAGE_Bm(1, 0, Bb, 1); STAGE_A(1, 0, Ab, 1); STAGE_Bm(1, 1, Bb, 1);
;       WAIT_V(6); BAR8;
.LBB0_514:
	s_or_b64 exec, exec, s[12:13]
	s_lshl_b32 s12, s73, 8
	v_lshl_add_u64 v[138:139], s[14:15], 0, v[4:5]
	s_mov_b64 s[14:15], 0x80
	s_add_i32 s73, s26, 0x18000
	v_lshl_add_u64 v[8:9], v[138:139], 0, s[14:15]
	s_mov_b32 m0, s73
	s_mov_b64 s[90:91], 0x40080
	s_add_i32 s74, s26, 0x1a000
	s_barrier
	global_load_lds_dwordx4 v[8:9], off
	v_lshl_add_u64 v[8:9], v[138:139], 0, s[90:91]
	s_mov_b32 m0, s74
	v_lshl_add_u64 v[136:137], s[16:17], 0, v[0:1]
	s_add_i32 s75, s26, 0x10000
	global_load_lds_dwordx4 v[8:9], off
	v_lshl_add_u64 v[8:9], v[136:137], 0, s[14:15]
	s_mov_b32 m0, s75
	s_mov_b64 s[14:15], 0x10080
	global_load_lds_dwordx4 v[8:9], off
	v_lshl_add_u64 v[8:9], v[136:137], 0, s[90:91]
	s_add_i32 s90, s26, 0x12000
	s_mov_b32 m0, s90
	s_add_i32 s91, s26, 0x1c000
	global_load_lds_dwordx4 v[8:9], off
	v_lshl_add_u64 v[8:9], v[138:139], 0, s[14:15]
	s_mov_b32 m0, s91
	s_mov_b64 s[14:15], 0x50080
	s_add_i32 s92, s26, 0x1e000
	global_load_lds_dwordx4 v[8:9], off
	v_lshl_add_u64 v[8:9], v[138:139], 0, s[14:15]
	s_mov_b32 m0, s92
	s_ashr_i32 s13, s12, 31
	global_load_lds_dwordx4 v[8:9], off
	s_mov_b64 s[14:15], 0x20000
	s_lshl_b32 s51, s51, 8
	s_waitcnt vmcnt(6)
	v_lshl_add_u64 v[140:141], v[136:137], 0, s[14:15]
	s_lshl_b64 s[14:15], s[12:13], 1
	s_add_u32 s14, s40, s14
	v_mov_b32_e32 v8, 0
	s_mov_b64 s[34:35], 0x40080
	v_lshl_add_u64 v[142:143], v[138:139], 0, s[44:45]
	s_addc_u32 s15, s41, s15
	s_mov_b32 s13, -2
	v_mov_b32_e32 v9, v8
	v_mov_b32_e32 v10, v8
	v_mov_b32_e32 v11, v8
	v_mov_b32_e32 v12, v8
	v_mov_b32_e32 v13, v8
	v_mov_b32_e32 v14, v8
	v_mov_b32_e32 v15, v8
	v_mov_b32_e32 v20, v8
	v_mov_b32_e32 v21, v8
	v_mov_b32_e32 v22, v8
	v_mov_b32_e32 v23, v8
	v_mov_b32_e32 v28, v8
	v_mov_b32_e32 v29, v8
	v_mov_b32_e32 v30, v8
	v_mov_b32_e32 v31, v8
	v_mov_b32_e32 v16, v8
	v_mov_b32_e32 v17, v8
	v_mov_b32_e32 v18, v8
	v_mov_b32_e32 v19, v8
	v_mov_b32_e32 v24, v8
	v_mov_b32_e32 v25, v8
	v_mov_b32_e32 v26, v8
	v_mov_b32_e32 v27, v8
	v_mov_b32_e32 v36, v8
	v_mov_b32_e32 v37, v8
	v_mov_b32_e32 v38, v8
	v_mov_b32_e32 v39, v8
	v_mov_b32_e32 v44, v8
	v_mov_b32_e32 v45, v8
	v_mov_b32_e32 v46, v8
	v_mov_b32_e32 v47, v8
	v_mov_b32_e32 v32, v8
	v_mov_b32_e32 v33, v8
	v_mov_b32_e32 v34, v8
	v_mov_b32_e32 v35, v8
	v_mov_b32_e32 v40, v8
	v_mov_b32_e32 v41, v8
	v_mov_b32_e32 v42, v8
	v_mov_b32_e32 v43, v8
	v_mov_b32_e32 v52, v8
	v_mov_b32_e32 v53, v8
	v_mov_b32_e32 v54, v8
	v_mov_b32_e32 v55, v8
	v_mov_b32_e32 v60, v8
	v_mov_b32_e32 v61, v8
	v_mov_b32_e32 v62, v8
	v_mov_b32_e32 v63, v8
	v_mov_b32_e32 v48, v8
	v_mov_b32_e32 v49, v8
	v_mov_b32_e32 v50, v8
	v_mov_b32_e32 v51, v8
	v_mov_b32_e32 v56, v8
	v_mov_b32_e32 v57, v8
	v_mov_b32_e32 v58, v8
	v_mov_b32_e32 v59, v8
	v_mov_b32_e32 v64, v8
	v_mov_b32_e32 v65, v8
	v_mov_b32_e32 v66, v8
	v_mov_b32_e32 v67, v8
	v_mov_b32_e32 v68, v8
	v_mov_b32_e32 v69, v8
	v_mov_b32_e32 v70, v8
	v_mov_b32_e32 v71, v8
	v_mov_b32_e32 v72, v8
	v_mov_b32_e32 v73, v8
	v_mov_b32_e32 v74, v8
	v_mov_b32_e32 v75, v8
	v_mov_b32_e32 v76, v8
	v_mov_b32_e32 v77, v8
	v_mov_b32_e32 v78, v8
	v_mov_b32_e32 v79, v8
	v_mov_b32_e32 v88, v8
	v_mov_b32_e32 v89, v8
	v_mov_b32_e32 v90, v8
	v_mov_b32_e32 v91, v8
	v_mov_b32_e32 v92, v8
	v_mov_b32_e32 v93, v8
	v_mov_b32_e32 v94, v8
	v_mov_b32_e32 v95, v8
	v_mov_b32_e32 v80, v8
	v_mov_b32_e32 v81, v8
	v_mov_b32_e32 v82, v8
	v_mov_b32_e32 v83, v8
	v_mov_b32_e32 v84, v8
	v_mov_b32_e32 v85, v8
	v_mov_b32_e32 v86, v8
	v_mov_b32_e32 v87, v8
	v_mov_b32_e32 v104, v8
	v_mov_b32_e32 v105, v8
	v_mov_b32_e32 v106, v8
	v_mov_b32_e32 v107, v8
	v_mov_b32_e32 v108, v8
	v_mov_b32_e32 v109, v8
	v_mov_b32_e32 v110, v8
	v_mov_b32_e32 v111, v8
	v_mov_b32_e32 v96, v8
	v_mov_b32_e32 v97, v8
	v_mov_b32_e32 v98, v8
	v_mov_b32_e32 v99, v8
	v_mov_b32_e32 v100, v8
	v_mov_b32_e32 v101, v8
	v_mov_b32_e32 v102, v8
	v_mov_b32_e32 v103, v8
	v_mov_b32_e32 v120, v8
	v_mov_b32_e32 v121, v8
	v_mov_b32_e32 v122, v8
	v_mov_b32_e32 v123, v8
	v_mov_b32_e32 v124, v8
	v_mov_b32_e32 v125, v8
	v_mov_b32_e32 v126, v8
	v_mov_b32_e32 v127, v8
	v_mov_b32_e32 v112, v8
	v_mov_b32_e32 v113, v8
	v_mov_b32_e32 v114, v8
	v_mov_b32_e32 v115, v8
	v_mov_b32_e32 v116, v8
	v_mov_b32_e32 v117, v8
	v_mov_b32_e32 v118, v8
	v_mov_b32_e32 v119, v8
	v_mov_b32_e32 v128, v8
	v_mov_b32_e32 v129, v8
	v_mov_b32_e32 v130, v8
	v_mov_b32_e32 v131, v8
	v_mov_b32_e32 v132, v8
	v_mov_b32_e32 v133, v8
	v_mov_b32_e32 v134, v8
	v_mov_b32_e32 v135, v8
	s_barrier
	s_branch .LBB0_516

; #define WAIT_V(n) asm volatile("s_waitcnt vmcnt(%0)" ::"n"(n) : "memory")
; #define BAR8 __builtin_amdgcn_s_barrier()
; template <int EPI> ...
;     ...
;     if constexpr (EPI == EPI_RES) {
; #pragma unroll
;       for (int m = 0; m < 8; ++m)
; #pragma unroll
;         for (int n = 0; n < 4; ++n) asm volatile("" : "+v"(acc[m][n]));
;     } else {
; #pragma unroll
;       for (int m = 0; m < 8; ++m)
; #pragma unroll
;         for (int n = 0; n < 4; ++n) acc[m][n] = f32x4{0.f, 0.f, 0.f, 0.f};
;     }
;     {
;       bf16x8 At[4][2], B0[2][2], B1[2][2];
;       if (wr == 1) BAR8;
;       BAR8;
;       STAGE_Bm(1, 0, Bb, 1); STAGE_A(1, 0, Ab, 1); STAGE_Bm(1, 1, Bb, 1);
;       WAIT_V(6); BAR8;
.LBB0_685:
	s_or_b64 exec, exec, s[26:27]
	v_lshl_add_u64 v[138:139], s[22:23], 0, v[4:5]
	s_mov_b64 s[22:23], 0x80
	s_add_i32 s26, s96, 0x18000
	v_lshl_add_u64 v[8:9], v[138:139], 0, s[22:23]
	s_mov_b32 m0, s26
	s_mov_b64 s[94:95], 0x40080
	s_add_i32 s27, s96, 0x1a000
	s_barrier
	global_load_lds_dwordx4 v[8:9], off
	v_lshl_add_u64 v[8:9], v[138:139], 0, s[94:95]
	s_mov_b32 m0, s27
	v_lshl_add_u64 v[136:137], s[24:25], 0, v[0:1]
	s_add_i32 s24, s96, 0x10000
	global_load_lds_dwordx4 v[8:9], off
	v_lshl_add_u64 v[8:9], v[136:137], 0, s[22:23]
	s_mov_b32 m0, s24
	s_add_i32 s25, s96, 0x12000
	global_load_lds_dwordx4 v[8:9], off
	v_lshl_add_u64 v[8:9], v[136:137], 0, s[94:95]
	s_mov_b32 m0, s25
	s_mov_b64 s[22:23], 0x10080
	s_add_i32 s94, s96, 0x1c000
	global_load_lds_dwordx4 v[8:9], off
	v_lshl_add_u64 v[8:9], v[138:139], 0, s[22:23]
	s_mov_b32 m0, s94
	s_mov_b64 s[22:23], 0x50080
	s_add_i32 s95, s96, 0x1e000
	global_load_lds_dwordx4 v[8:9], off
	v_lshl_add_u64 v[8:9], v[138:139], 0, s[22:23]
	s_mov_b32 m0, s95
	s_mov_b64 s[22:23], 0x20000
	global_load_lds_dwordx4 v[8:9], off
	v_mov_b32_e32 v8, 0
	s_mov_b64 s[34:35], 0x40080
	v_lshl_add_u64 v[140:141], v[136:137], 0, s[22:23]
	v_lshl_add_u64 v[142:143], v[138:139], 0, s[44:45]
	s_mov_b32 vcc_lo, -2
	v_mov_b32_e32 v9, v8
	v_mov_b32_e32 v10, v8
	v_mov_b32_e32 v11, v8
	v_mov_b32_e32 v12, v8
	v_mov_b32_e32 v13, v8
	v_mov_b32_e32 v14, v8
	v_mov_b32_e32 v15, v8
	v_mov_b32_e32 v24, v8
	v_mov_b32_e32 v25, v8
	v_mov_b32_e32 v26, v8
	v_mov_b32_e32 v27, v8
	v_mov_b32_e32 v28, v8
	v_mov_b32_e32 v29, v8
	v_mov_b32_e32 v30, v8
	v_mov_b32_e32 v31, v8
	v_mov_b32_e32 v16, v8
	v_mov_b32_e32 v17, v8
	v_mov_b32_e32 v18, v8
	v_mov_b32_e32 v19, v8
	v_mov_b32_e32 v20, v8
	v_mov_b32_e32 v21, v8
	v_mov_b32_e32 v22, v8
	v_mov_b32_e32 v23, v8
	v_mov_b32_e32 v48, v8
	v_mov_b32_e32 v49, v8
	v_mov_b32_e32 v50, v8
	v_mov_b32_e32 v51, v8
	v_mov_b32_e32 v64, v8
	v_mov_b32_e32 v65, v8
	v_mov_b32_e32 v66, v8
	v_mov_b32_e32 v67, v8
	v_mov_b32_e32 v36, v8
	v_mov_b32_e32 v37, v8
	v_mov_b32_e32 v38, v8
	v_mov_b32_e32 v39, v8
	v_mov_b32_e32 v44, v8
	v_mov_b32_e32 v45, v8
	v_mov_b32_e32 v46, v8
	v_mov_b32_e32 v47, v8
	v_mov_b32_e32 v96, v8
	v_mov_b32_e32 v97, v8
	v_mov_b32_e32 v98, v8
	v_mov_b32_e32 v99, v8
	v_mov_b32_e32 v100, v8
	v_mov_b32_e32 v101, v8
	v_mov_b32_e32 v102, v8
	v_mov_b32_e32 v103, v8
	v_mov_b32_e32 v72, v8
	v_mov_b32_e32 v73, v8
	v_mov_b32_e32 v74, v8
	v_mov_b32_e32 v75, v8
	v_mov_b32_e32 v92, v8
	v_mov_b32_e32 v93, v8
	v_mov_b32_e32 v94, v8
	v_mov_b32_e32 v95, v8
	v_mov_b32_e32 v124, v8
	v_mov_b32_e32 v125, v8
	v_mov_b32_e32 v126, v8
	v_mov_b32_e32 v127, v8
	v_mov_b32_e32 v132, v8
	v_mov_b32_e32 v133, v8
	v_mov_b32_e32 v134, v8
	v_mov_b32_e32 v135, v8
	v_mov_b32_e32 v52, v8
	v_mov_b32_e32 v53, v8
	v_mov_b32_e32 v54, v8
	v_mov_b32_e32 v55, v8
	v_mov_b32_e32 v56, v8
	v_mov_b32_e32 v57, v8
	v_mov_b32_e32 v58, v8
	v_mov_b32_e32 v59, v8
	v_mov_b32_e32 v32, v8
	v_mov_b32_e32 v33, v8
	v_mov_b32_e32 v34, v8
	v_mov_b32_e32 v35, v8
	v_mov_b32_e32 v40, v8
	v_mov_b32_e32 v41, v8
	v_mov_b32_e32 v42, v8
	v_mov_b32_e32 v43, v8
	v_mov_b32_e32 v76, v8
	v_mov_b32_e32 v77, v8
	v_mov_b32_e32 v78, v8
	v_mov_b32_e32 v79, v8
	v_mov_b32_e32 v80, v8
	v_mov_b32_e32 v81, v8
	v_mov_b32_e32 v82, v8
	v_mov_b32_e32 v83, v8
	v_mov_b32_e32 v60, v8
	v_mov_b32_e32 v61, v8
	v_mov_b32_e32 v62, v8
	v_mov_b32_e32 v63, v8
	v_mov_b32_e32 v68, v8
	v_mov_b32_e32 v69, v8
	v_mov_b32_e32 v70, v8
	v_mov_b32_e32 v71, v8
	v_mov_b32_e32 v104, v8
	v_mov_b32_e32 v105, v8
	v_mov_b32_e32 v106, v8
	v_mov_b32_e32 v107, v8
	v_mov_b32_e32 v108, v8
	v_mov_b32_e32 v109, v8
	v_mov_b32_e32 v110, v8
	v_mov_b32_e32 v111, v8
	v_mov_b32_e32 v84, v8
	v_mov_b32_e32 v85, v8
	v_mov_b32_e32 v86, v8
	v_mov_b32_e32 v87, v8
	v_mov_b32_e32 v88, v8
	v_mov_b32_e32 v89, v8
	v_mov_b32_e32 v90, v8
	v_mov_b32_e32 v91, v8
	v_mov_b32_e32 v120, v8
	v_mov_b32_e32 v121, v8
	v_mov_b32_e32 v122, v8
	v_mov_b32_e32 v123, v8
	v_mov_b32_e32 v128, v8
	v_mov_b32_e32 v129, v8
	v_mov_b32_e32 v130, v8
	v_mov_b32_e32 v131, v8
	v_mov_b32_e32 v112, v8
	v_mov_b32_e32 v113, v8
	v_mov_b32_e32 v114, v8
	v_mov_b32_e32 v115, v8
	v_mov_b32_e32 v116, v8
	v_mov_b32_e32 v117, v8
	v_mov_b32_e32 v118, v8
	v_mov_b32_e32 v119, v8
	s_barrier
